# PD fused epilogue: gain vector loaded once, residual half-rows loaded in pairs (24 fewer serialized round trips per tile)
# speedup vs baseline: 1.0059x; 1.0059x over previous
; #define LAS __attribute__((address_space(3)))
;     __device__ __forceinline__ void exchange(int e, float (&sv)[2][4], float (&rv)[2][4], const Unit& u, int wr, int wc, int fr, int fq, LAS unsigned char* lds, int wid, int lane) const {
;     ...
; #pragma unroll
;         for (int ai = 0; ai < 2; ++ai)
; #pragma unroll
;             for (int m = 0; m < 4; ++m) rv[ai][m] = Sx[ai * HALF + wr * 64 + m * 16 + fr];
;     }
;     __device__ __forceinline__ void fused(f32x4 (&acc)[2][2][4][2], const Unit& u, int wr, int wc, int fr, int fq, LAS unsigned char* lds, int wid, int lane) const {
;         bf16_t* hb = (bf16_t*)(ws + WS_HB);
;         const int row0 = u.pm * BM + wr * 64 + fr, col0 = u.pn * BM + wc * 32 + 8 * fq;
;         float sv[2][4], rv[2][4];
; #pragma unroll
;         for (int ai = 0; ai < 2; ++ai)
; #pragma unroll
;             for (int m = 0; m < 4; ++m) {
;                 float q = 0.f;
; #pragma unroll
;                 for (int bj = 0; bj < 2; ++bj)
; #pragma unroll
;                     for (int n = 0; n < 2; ++n) { const f32x4 x = acc[ai][bj][m][n]; q += (x[0] * x[0] + x[1] * x[1]) + (x[2] * x[2] + x[3] * x[3]); }
;                 sv[ai][m] = q;
;             }
;         exchange(0, sv, rv, u, wr, wc, fr, fq, lds, wid, lane);
;         float dep = 0.f;
; #pragma unroll
;         for (int ai = 0; ai < 2; ++ai)
; #pragma unroll
;             for (int m = 0; m < 4; ++m) {
;                 const bf16_t* hrow = hb + (size_t)(row0 + ai * HALF + m * 16) * DM + col0;
;                 asm volatile("" : "+v"(hrow) : "v"(dep));
;                 const float r1 = rv[ai][m];
;                 float q = 0.f;
; #pragma unroll
;                 for (int bj = 0; bj < 2; ++bj) {
;                     const u32x4 hv = *(const u32x4*)(hrow + bj * HALF);
;                     const f32x4 h0 = (f32x4){__uint_as_float(hv.x << 16), __uint_as_float(hv.x & 0xffff0000u), __uint_as_float(hv.y << 16), __uint_as_float(hv.y & 0xffff0000u)};
;                     const f32x4 h1 = (f32x4){__uint_as_float(hv.z << 16), __uint_as_float(hv.z & 0xffff0000u), __uint_as_float(hv.w << 16), __uint_as_float(hv.w & 0xffff0000u)};
;                     const f32x4 gg0 = *(const f32x4*)(gpost + col0 + bj * HALF), gg1 = *(const f32x4*)(gpost + col0 + bj * HALF + 4);
;                     f32x4 x0 = h0 + acc[ai][bj][m][0] * r1 * gg0, x1 = h1 + acc[ai][bj][m][1] * r1 * gg1;
.LBB0_1434:
	s_or_b64 exec, exec, s[42:43]
	v_lshl_add_u32 v146, s28, 8, v1
	v_lshl_or_b32 v156, s26, 8, v208
	v_ashrrev_i32_e32 v157, 31, v156
	v_ashrrev_i32_e32 v147, 31, v146
	v_lshl_add_u64 v[158:159], v[156:157], 1, s[22:23]
	v_lshlrev_b64 v[148:149], 11, v[146:147]
	v_lshl_add_u64 v[148:149], v[158:159], 0, v[148:149]
	s_waitcnt vmcnt(0) lgkmcnt(0)
	s_barrier
	v_mov_b64_e32 v[166:167], v[148:149]
	ds_read2_b32 v[160:161], v214 offset1:16
	ds_read2_b32 v[170:171], v214 offset0:32 offset1:48
	ds_read2_b32 v[168:169], v214 offset0:128 offset1:144
	ds_read2_b32 v[154:155], v214 offset0:160 offset1:176
	flat_load_dwordx4 v[150:153], v[166:167]
	flat_load_dwordx4 v[232:235], v[166:167] offset:256
	v_lshl_add_u64 v[156:157], v[156:157], 2, s[14:15]
	global_load_dwordx4 v[236:239], v[156:157], off
	global_load_dwordx4 v[240:243], v[156:157], off offset:16
	global_load_dwordx4 v[244:247], v[156:157], off offset:512
	global_load_dwordx4 v[248:251], v[156:157], off offset:528
	s_waitcnt lgkmcnt(0)
	v_pk_mul_f32 v[128:129], v[128:129], v[160:161] op_sel_hi:[1,0]
	v_pk_mul_f32 v[182:183], v[126:127], v[160:161] op_sel_hi:[1,0]
	v_pk_mul_f32 v[124:125], v[124:125], v[160:161] op_sel_hi:[1,0]
	v_pk_mul_f32 v[120:121], v[120:121], v[160:161] op_sel_hi:[1,0]
	v_pk_mul_f32 v[116:117], v[116:117], v[160:161] op_sel_hi:[1,0]
	v_mov_b32_e32 v186, v161
	v_pk_mul_f32 v[112:113], v[112:113], v[186:187] op_sel_hi:[1,0]
	v_pk_mul_f32 v[108:109], v[108:109], v[186:187] op_sel_hi:[1,0]
	v_pk_mul_f32 v[104:105], v[104:105], v[186:187] op_sel_hi:[1,0]
	v_pk_mul_f32 v[100:101], v[100:101], v[186:187] op_sel_hi:[1,0]
	v_pk_mul_f32 v[96:97], v[96:97], v[170:171] op_sel_hi:[1,0]
	v_pk_mul_f32 v[188:189], v[94:95], v[170:171] op_sel_hi:[1,0]
	v_pk_mul_f32 v[92:93], v[92:93], v[170:171] op_sel_hi:[1,0]
	v_pk_mul_f32 v[88:89], v[88:89], v[170:171] op_sel_hi:[1,0]
	v_pk_mul_f32 v[84:85], v[84:85], v[170:171] op_sel_hi:[1,0]
	v_mov_b32_e32 v192, v171
	v_pk_mul_f32 v[80:81], v[80:81], v[192:193] op_sel_hi:[1,0]
	v_pk_mul_f32 v[76:77], v[76:77], v[192:193] op_sel_hi:[1,0]
	v_pk_mul_f32 v[72:73], v[72:73], v[192:193] op_sel_hi:[1,0]
	v_pk_mul_f32 v[68:69], v[68:69], v[192:193] op_sel_hi:[1,0]
	v_pk_mul_f32 v[64:65], v[64:65], v[168:169] op_sel_hi:[1,0]
	v_pk_mul_f32 v[194:195], v[62:63], v[168:169] op_sel_hi:[1,0]
	v_pk_mul_f32 v[60:61], v[60:61], v[168:169] op_sel_hi:[1,0]
	v_pk_mul_f32 v[56:57], v[56:57], v[168:169] op_sel_hi:[1,0]
	v_pk_mul_f32 v[52:53], v[52:53], v[168:169] op_sel_hi:[1,0]
	v_mov_b32_e32 v198, v169
	v_pk_mul_f32 v[48:49], v[48:49], v[198:199] op_sel_hi:[1,0]
	v_pk_mul_f32 v[44:45], v[44:45], v[198:199] op_sel_hi:[1,0]
	v_pk_mul_f32 v[38:39], v[38:39], v[198:199] op_sel_hi:[1,0]
	v_pk_mul_f32 v[40:41], v[40:41], v[198:199] op_sel_hi:[1,0]
	v_pk_mul_f32 v[36:37], v[36:37], v[198:199] op_sel_hi:[1,0]
	v_pk_mul_f32 v[34:35], v[34:35], v[198:199] op_sel_hi:[1,0]
	v_pk_mul_f32 v[32:33], v[32:33], v[154:155] op_sel_hi:[1,0]
	v_pk_mul_f32 v[28:29], v[28:29], v[154:155] op_sel_hi:[1,0]
	v_pk_mul_f32 v[26:27], v[26:27], v[154:155] op_sel_hi:[1,0]
	v_pk_mul_f32 v[30:31], v[30:31], v[154:155] op_sel_hi:[1,0]
	v_pk_mul_f32 v[22:23], v[22:23], v[154:155] op_sel_hi:[1,0]
	v_pk_mul_f32 v[24:25], v[24:25], v[154:155] op_sel_hi:[1,0]
	v_pk_mul_f32 v[20:21], v[20:21], v[154:155] op_sel_hi:[1,0]
	v_pk_mul_f32 v[18:19], v[18:19], v[154:155] op_sel_hi:[1,0]
	v_add_u32_e32 v206, 0xb0, v146
	v_ashrrev_i32_e32 v207, 31, v206
	s_waitcnt vmcnt(0)
	v_lshlrev_b32_e32 v172, 16, v150
	v_and_b32_e32 v173, 0xffff0000, v150
	v_lshlrev_b32_e32 v174, 16, v151
	v_and_b32_e32 v175, 0xffff0000, v151
	v_lshlrev_b32_e32 v176, 16, v152
	v_and_b32_e32 v177, 0xffff0000, v152
	v_lshlrev_b32_e32 v178, 16, v153
	v_and_b32_e32 v179, 0xffff0000, v153
	v_mov_b64_e32 v[150:151], v[240:241]
	v_mov_b64_e32 v[152:153], v[242:243]
	v_mov_b64_e32 v[162:163], v[236:237]
	v_mov_b64_e32 v[164:165], v[238:239]
	s_waitcnt vmcnt(0)
	v_pk_fma_f32 v[126:127], v[128:129], v[164:165], v[174:175]
	v_pk_fma_f32 v[128:129], v[182:183], v[162:163], v[172:173]
	v_pk_mul_f32 v[162:163], v[122:123], v[160:161] op_sel_hi:[1,0]
	v_pk_fma_f32 v[122:123], v[124:125], v[152:153], v[178:179]
	v_pk_fma_f32 v[124:125], v[162:163], v[150:151], v[176:177]
	v_mov_b64_e32 v[150:151], v[232:233]
	v_mov_b64_e32 v[152:153], v[234:235]
	v_pk_mul_f32 v[178:179], v[118:119], v[160:161] op_sel_hi:[1,0]
	s_waitcnt vmcnt(0) lgkmcnt(0)
	v_lshlrev_b32_e32 v166, 16, v150
	v_and_b32_e32 v167, 0xffff0000, v150
	v_lshlrev_b32_e32 v172, 16, v151
	v_and_b32_e32 v173, 0xffff0000, v151
	v_lshlrev_b32_e32 v174, 16, v152
	v_and_b32_e32 v175, 0xffff0000, v152
	v_lshlrev_b32_e32 v176, 16, v153
	v_and_b32_e32 v177, 0xffff0000, v153
	v_mov_b64_e32 v[150:151], v[248:249]
	v_mov_b64_e32 v[152:153], v[250:251]
	v_mov_b64_e32 v[162:163], v[244:245]
	v_mov_b64_e32 v[164:165], v[246:247]
	s_waitcnt vmcnt(0)
;     __device__ __forceinline__ void fused(f32x4 (&acc)[2][2][4][2], const Unit& u, int wr, int wc, int fr, int fq, LAS unsigned char* lds, int wid, int lane) const {
;     ...
; #pragma unroll
;             for (int m = 0; m < 4; ++m) {
;                 const bf16_t* hrow = hb + (size_t)(row0 + ai * HALF + m * 16) * DM + col0;
;                 asm volatile("" : "+v"(hrow) : "v"(dep));
;                 const float r1 = rv[ai][m];
;                 float q = 0.f;
; #pragma unroll
;                 for (int bj = 0; bj < 2; ++bj) {
;                     const u32x4 hv = *(const u32x4*)(hrow + bj * HALF);
;                     const f32x4 h0 = (f32x4){__uint_as_float(hv.x << 16), __uint_as_float(hv.x & 0xffff0000u), __uint_as_float(hv.y << 16), __uint_as_float(hv.y & 0xffff0000u)};
;                     const f32x4 h1 = (f32x4){__uint_as_float(hv.z << 16), __uint_as_float(hv.z & 0xffff0000u), __uint_as_float(hv.w << 16), __uint_as_float(hv.w & 0xffff0000u)};
;                     const f32x4 gg0 = *(const f32x4*)(gpost + col0 + bj * HALF), gg1 = *(const f32x4*)(gpost + col0 + bj * HALF + 4);
;                     f32x4 x0 = h0 + acc[ai][bj][m][0] * r1 * gg0, x1 = h1 + acc[ai][bj][m][1] * r1 * gg1;
;                     acc[ai][bj][m][0] = x0; acc[ai][bj][m][1] = x1;
;                     q += ((x0[0] * x0[0] + x0[1] * x0[1]) + (x0[2] * x0[2] + x0[3] * x0[3])) + ((x1[0] * x1[0] + x1[1] * x1[1]) + (x1[2] * x1[2] + x1[3] * x1[3]));
;                 }
;                 sv[ai][m] = q;
;                 dep = q;
	v_pk_fma_f32 v[118:119], v[120:121], v[164:165], v[172:173]
	v_pk_fma_f32 v[120:121], v[178:179], v[162:163], v[166:167]
	v_pk_mul_f32 v[162:163], v[114:115], v[160:161] op_sel_hi:[1,0]
	v_pk_fma_f32 v[114:115], v[116:117], v[152:153], v[176:177]
	v_mov_b32_e32 v152, v129
	v_mov_b32_e32 v153, v121
	v_pk_fma_f32 v[116:117], v[162:163], v[150:151], v[174:175]
	v_mov_b32_e32 v150, v128
	v_mov_b32_e32 v151, v120
	v_pk_mul_f32 v[152:153], v[152:153], v[152:153]
	v_mov_b32_e32 v162, v127
	v_mov_b32_e32 v163, v119
	v_pk_fma_f32 v[150:151], v[150:151], v[150:151], v[152:153]
	v_mov_b32_e32 v152, v126
	v_mov_b32_e32 v153, v118
	v_pk_mul_f32 v[162:163], v[162:163], v[162:163]
	v_mov_b32_e32 v164, v123
	v_pk_fma_f32 v[152:153], v[152:153], v[152:153], v[162:163]
	v_mov_b32_e32 v162, v125
	v_mov_b32_e32 v163, v117
	v_pk_add_f32 v[150:151], v[150:151], v[152:153]
	v_mov_b32_e32 v152, v124
	v_mov_b32_e32 v153, v116
	v_pk_mul_f32 v[162:163], v[162:163], v[162:163]
	v_mov_b32_e32 v165, v115
	v_pk_fma_f32 v[152:153], v[152:153], v[152:153], v[162:163]
	v_mov_b32_e32 v162, v122
	v_mov_b32_e32 v163, v114
	v_pk_mul_f32 v[164:165], v[164:165], v[164:165]
	v_pk_mul_f32 v[160:161], v[110:111], v[186:187] op_sel_hi:[1,0]
	v_pk_fma_f32 v[162:163], v[162:163], v[162:163], v[164:165]
	s_nop 0
	v_pk_add_f32 v[152:153], v[152:153], v[162:163]
	s_nop 0
	v_pk_add_f32 v[150:151], v[150:151], v[152:153]
	s_nop 0
	v_add_f32_e32 v216, v150, v151
	v_or_b32_e32 v150, 16, v146
	v_ashrrev_i32_e32 v151, 31, v150
	v_lshlrev_b64 v[152:153], 11, v[150:151]
	v_lshl_add_u64 v[152:153], v[158:159], 0, v[152:153]
	v_mov_b64_e32 v[162:163], v[152:153]
	flat_load_dwordx4 v[164:167], v[162:163]
	flat_load_dwordx4 v[232:235], v[162:163] offset:256
	s_waitcnt vmcnt(0) lgkmcnt(0)
	v_lshlrev_b32_e32 v176, 16, v164
	v_and_b32_e32 v177, 0xffff0000, v164
	v_lshlrev_b32_e32 v178, 16, v165
	v_and_b32_e32 v179, 0xffff0000, v165
	v_lshlrev_b32_e32 v182, 16, v166
	v_and_b32_e32 v183, 0xffff0000, v166
	v_lshlrev_b32_e32 v184, 16, v167
	v_and_b32_e32 v185, 0xffff0000, v167
	v_mov_b64_e32 v[164:165], v[240:241]
	v_mov_b64_e32 v[166:167], v[242:243]
	v_mov_b64_e32 v[172:173], v[236:237]
	v_mov_b64_e32 v[174:175], v[238:239]
	s_waitcnt vmcnt(0)
	v_pk_fma_f32 v[110:111], v[112:113], v[174:175], v[178:179]
	v_pk_fma_f32 v[112:113], v[160:161], v[172:173], v[176:177]
	v_pk_mul_f32 v[160:161], v[106:107], v[186:187] op_sel_hi:[1,0]
	v_pk_fma_f32 v[106:107], v[108:109], v[166:167], v[184:185]
	v_pk_fma_f32 v[108:109], v[160:161], v[164:165], v[182:183]
	v_mov_b64_e32 v[160:161], v[232:233]
	v_mov_b64_e32 v[162:163], v[234:235]
	v_pk_mul_f32 v[182:183], v[102:103], v[186:187] op_sel_hi:[1,0]
	s_waitcnt vmcnt(0) lgkmcnt(0)
	v_lshlrev_b32_e32 v172, 16, v160
	v_and_b32_e32 v173, 0xffff0000, v160
	v_lshlrev_b32_e32 v174, 16, v161
	v_and_b32_e32 v175, 0xffff0000, v161
	v_lshlrev_b32_e32 v176, 16, v162
	v_and_b32_e32 v177, 0xffff0000, v162
	v_lshlrev_b32_e32 v178, 16, v163
	v_and_b32_e32 v179, 0xffff0000, v163
	v_mov_b64_e32 v[160:161], v[248:249]
	v_mov_b64_e32 v[162:163], v[250:251]
	v_mov_b64_e32 v[164:165], v[244:245]
	v_mov_b64_e32 v[166:167], v[246:247]
	s_waitcnt vmcnt(0)
	v_pk_fma_f32 v[102:103], v[104:105], v[166:167], v[174:175]
	v_pk_fma_f32 v[104:105], v[182:183], v[164:165], v[172:173]
	v_pk_mul_f32 v[164:165], v[98:99], v[186:187] op_sel_hi:[1,0]
	v_pk_fma_f32 v[98:99], v[100:101], v[162:163], v[178:179]
	v_mov_b32_e32 v162, v113
	v_mov_b32_e32 v163, v105
	v_pk_fma_f32 v[100:101], v[164:165], v[160:161], v[176:177]
	v_mov_b32_e32 v160, v112
	v_mov_b32_e32 v161, v104
	v_pk_mul_f32 v[162:163], v[162:163], v[162:163]
	v_mov_b32_e32 v164, v111
	v_mov_b32_e32 v165, v103
	v_pk_fma_f32 v[160:161], v[160:161], v[160:161], v[162:163]
	v_mov_b32_e32 v162, v110
	v_mov_b32_e32 v163, v102
	v_pk_mul_f32 v[164:165], v[164:165], v[164:165]
	v_mov_b32_e32 v166, v107
	v_pk_fma_f32 v[162:163], v[162:163], v[162:163], v[164:165]
	v_mov_b32_e32 v164, v109
	v_mov_b32_e32 v165, v101
	v_pk_add_f32 v[160:161], v[160:161], v[162:163]
	v_mov_b32_e32 v162, v108
	v_mov_b32_e32 v163, v100
	v_pk_mul_f32 v[164:165], v[164:165], v[164:165]
	v_mov_b32_e32 v167, v99
	v_pk_fma_f32 v[162:163], v[162:163], v[162:163], v[164:165]
	v_mov_b32_e32 v164, v106
	v_mov_b32_e32 v165, v98
	v_pk_mul_f32 v[166:167], v[166:167], v[166:167]
	s_nop 0
	v_pk_fma_f32 v[164:165], v[164:165], v[164:165], v[166:167]
	s_nop 0
	v_pk_add_f32 v[162:163], v[162:163], v[164:165]
	s_nop 0
	v_pk_add_f32 v[160:161], v[160:161], v[162:163]
	s_nop 0
	v_add_f32_e32 v217, v160, v161
	v_or_b32_e32 v160, 32, v146
	v_ashrrev_i32_e32 v161, 31, v160
	v_lshlrev_b64 v[162:163], 11, v[160:161]
	v_lshl_add_u64 v[162:163], v[158:159], 0, v[162:163]
	v_mov_b64_e32 v[164:165], v[162:163]
	flat_load_dwordx4 v[172:175], v[164:165]
	flat_load_dwordx4 v[232:235], v[164:165] offset:256
	s_waitcnt vmcnt(0) lgkmcnt(0)
	v_lshlrev_b32_e32 v166, 16, v172
	v_and_b32_e32 v167, 0xffff0000, v172
	v_lshlrev_b32_e32 v182, 16, v173
	v_and_b32_e32 v183, 0xffff0000, v173
	v_lshlrev_b32_e32 v184, 16, v174
	v_and_b32_e32 v185, 0xffff0000, v174
	v_lshlrev_b32_e32 v186, 16, v175
	v_and_b32_e32 v187, 0xffff0000, v175
	v_mov_b64_e32 v[172:173], v[240:241]
	v_mov_b64_e32 v[174:175], v[242:243]
	v_mov_b64_e32 v[176:177], v[236:237]
	v_mov_b64_e32 v[178:179], v[238:239]
	s_waitcnt vmcnt(0)
	v_pk_fma_f32 v[94:95], v[96:97], v[178:179], v[182:183]
	v_pk_fma_f32 v[96:97], v[188:189], v[176:177], v[166:167]
	v_pk_mul_f32 v[166:167], v[90:91], v[170:171] op_sel_hi:[1,0]
	v_pk_fma_f32 v[90:91], v[92:93], v[174:175], v[186:187]
	v_pk_fma_f32 v[92:93], v[166:167], v[172:173], v[184:185]
	v_mov_b64_e32 v[164:165], v[232:233]
	v_mov_b64_e32 v[166:167], v[234:235]
	v_pk_mul_f32 v[186:187], v[86:87], v[170:171] op_sel_hi:[1,0]
	s_waitcnt vmcnt(0) lgkmcnt(0)
;     __device__ __forceinline__ void fused(f32x4 (&acc)[2][2][4][2], const Unit& u, int wr, int wc, int fr, int fq, LAS unsigned char* lds, int wid, int lane) const {
;     ...
; #pragma unroll
;             for (int m = 0; m < 4; ++m) {
;                 const bf16_t* hrow = hb + (size_t)(row0 + ai * HALF + m * 16) * DM + col0;
;                 asm volatile("" : "+v"(hrow) : "v"(dep));
;                 const float r1 = rv[ai][m];
;                 float q = 0.f;
; #pragma unroll
;                 for (int bj = 0; bj < 2; ++bj) {
;                     const u32x4 hv = *(const u32x4*)(hrow + bj * HALF);
;                     const f32x4 h0 = (f32x4){__uint_as_float(hv.x << 16), __uint_as_float(hv.x & 0xffff0000u), __uint_as_float(hv.y << 16), __uint_as_float(hv.y & 0xffff0000u)};
;                     const f32x4 h1 = (f32x4){__uint_as_float(hv.z << 16), __uint_as_float(hv.z & 0xffff0000u), __uint_as_float(hv.w << 16), __uint_as_float(hv.w & 0xffff0000u)};
;                     const f32x4 gg0 = *(const f32x4*)(gpost + col0 + bj * HALF), gg1 = *(const f32x4*)(gpost + col0 + bj * HALF + 4);
;                     f32x4 x0 = h0 + acc[ai][bj][m][0] * r1 * gg0, x1 = h1 + acc[ai][bj][m][1] * r1 * gg1;
;                     acc[ai][bj][m][0] = x0; acc[ai][bj][m][1] = x1;
;                     q += ((x0[0] * x0[0] + x0[1] * x0[1]) + (x0[2] * x0[2] + x0[3] * x0[3])) + ((x1[0] * x1[0] + x1[1] * x1[1]) + (x1[2] * x1[2] + x1[3] * x1[3]));
;                 }
;                 sv[ai][m] = q;
;                 dep = q;
	v_lshlrev_b32_e32 v176, 16, v164
	v_and_b32_e32 v177, 0xffff0000, v164
	v_lshlrev_b32_e32 v178, 16, v165
	v_and_b32_e32 v179, 0xffff0000, v165
	v_lshlrev_b32_e32 v182, 16, v166
	v_and_b32_e32 v183, 0xffff0000, v166
	v_lshlrev_b32_e32 v184, 16, v167
	v_and_b32_e32 v185, 0xffff0000, v167
	v_mov_b64_e32 v[164:165], v[248:249]
	v_mov_b64_e32 v[166:167], v[250:251]
	v_mov_b64_e32 v[172:173], v[244:245]
	v_mov_b64_e32 v[174:175], v[246:247]
	s_waitcnt vmcnt(0)
	v_pk_fma_f32 v[86:87], v[88:89], v[174:175], v[178:179]
	v_pk_fma_f32 v[88:89], v[186:187], v[172:173], v[176:177]
	v_pk_mul_f32 v[172:173], v[82:83], v[170:171] op_sel_hi:[1,0]
	v_pk_fma_f32 v[82:83], v[84:85], v[166:167], v[184:185]
	v_mov_b32_e32 v166, v97
	v_mov_b32_e32 v167, v89
	v_pk_fma_f32 v[84:85], v[172:173], v[164:165], v[182:183]
	v_mov_b32_e32 v164, v96
	v_mov_b32_e32 v165, v88
	v_pk_mul_f32 v[166:167], v[166:167], v[166:167]
	v_mov_b32_e32 v172, v95
	v_mov_b32_e32 v173, v87
	v_pk_fma_f32 v[164:165], v[164:165], v[164:165], v[166:167]
	v_mov_b32_e32 v166, v94
	v_mov_b32_e32 v167, v86
	v_pk_mul_f32 v[172:173], v[172:173], v[172:173]
	v_mov_b32_e32 v174, v91
	v_pk_fma_f32 v[166:167], v[166:167], v[166:167], v[172:173]
	v_mov_b32_e32 v172, v93
	v_mov_b32_e32 v173, v85
	v_pk_add_f32 v[164:165], v[164:165], v[166:167]
	v_mov_b32_e32 v166, v92
	v_mov_b32_e32 v167, v84
	v_pk_mul_f32 v[172:173], v[172:173], v[172:173]
	v_mov_b32_e32 v175, v83
	v_pk_fma_f32 v[166:167], v[166:167], v[166:167], v[172:173]
	v_mov_b32_e32 v172, v90
	v_mov_b32_e32 v173, v82
	v_pk_mul_f32 v[174:175], v[174:175], v[174:175]
	v_pk_mul_f32 v[170:171], v[78:79], v[192:193] op_sel_hi:[1,0]
	v_pk_fma_f32 v[172:173], v[172:173], v[172:173], v[174:175]
	s_nop 0
	v_pk_add_f32 v[166:167], v[166:167], v[172:173]
	s_nop 0
	v_pk_add_f32 v[164:165], v[164:165], v[166:167]
	s_nop 0
	v_add_f32_e32 v218, v164, v165
	v_or_b32_e32 v164, 48, v146
	v_ashrrev_i32_e32 v165, 31, v164
	v_lshlrev_b64 v[166:167], 11, v[164:165]
	v_lshl_add_u64 v[166:167], v[158:159], 0, v[166:167]
	v_mov_b64_e32 v[172:173], v[166:167]
	flat_load_dwordx4 v[174:177], v[172:173]
	flat_load_dwordx4 v[232:235], v[172:173] offset:256
	s_waitcnt vmcnt(0) lgkmcnt(0)
	v_lshlrev_b32_e32 v178, 16, v174
	v_and_b32_e32 v179, 0xffff0000, v174
	v_lshlrev_b32_e32 v186, 16, v175
	v_and_b32_e32 v187, 0xffff0000, v175
	v_lshlrev_b32_e32 v188, 16, v176
	v_and_b32_e32 v189, 0xffff0000, v176
	v_lshlrev_b32_e32 v190, 16, v177
	v_and_b32_e32 v191, 0xffff0000, v177
	v_mov_b64_e32 v[174:175], v[240:241]
	v_mov_b64_e32 v[176:177], v[242:243]
	v_mov_b64_e32 v[182:183], v[236:237]
	v_mov_b64_e32 v[184:185], v[238:239]
	s_waitcnt vmcnt(0)
	v_pk_fma_f32 v[78:79], v[80:81], v[184:185], v[186:187]
	v_pk_fma_f32 v[80:81], v[170:171], v[182:183], v[178:179]
	v_pk_mul_f32 v[170:171], v[74:75], v[192:193] op_sel_hi:[1,0]
	v_pk_fma_f32 v[74:75], v[76:77], v[176:177], v[190:191]
	v_pk_fma_f32 v[76:77], v[170:171], v[174:175], v[188:189]
	v_mov_b64_e32 v[170:171], v[232:233]
	v_mov_b64_e32 v[172:173], v[234:235]
	v_pk_mul_f32 v[188:189], v[70:71], v[192:193] op_sel_hi:[1,0]
	s_waitcnt vmcnt(0) lgkmcnt(0)
	v_lshlrev_b32_e32 v178, 16, v170
	v_and_b32_e32 v179, 0xffff0000, v170
	v_lshlrev_b32_e32 v182, 16, v171
	v_and_b32_e32 v183, 0xffff0000, v171
	v_lshlrev_b32_e32 v184, 16, v172
	v_and_b32_e32 v185, 0xffff0000, v172
	v_lshlrev_b32_e32 v186, 16, v173
	v_and_b32_e32 v187, 0xffff0000, v173
	v_mov_b64_e32 v[170:171], v[248:249]
	v_mov_b64_e32 v[172:173], v[250:251]
	v_mov_b64_e32 v[174:175], v[244:245]
	v_mov_b64_e32 v[176:177], v[246:247]
	s_waitcnt vmcnt(0)
	v_pk_fma_f32 v[70:71], v[72:73], v[176:177], v[182:183]
	v_pk_fma_f32 v[72:73], v[188:189], v[174:175], v[178:179]
	v_pk_mul_f32 v[174:175], v[66:67], v[192:193] op_sel_hi:[1,0]
	v_pk_fma_f32 v[66:67], v[68:69], v[172:173], v[186:187]
	v_mov_b32_e32 v172, v81
	v_mov_b32_e32 v173, v73
	v_pk_fma_f32 v[68:69], v[174:175], v[170:171], v[184:185]
	v_mov_b32_e32 v170, v80
	v_mov_b32_e32 v171, v72
	v_pk_mul_f32 v[172:173], v[172:173], v[172:173]
	v_mov_b32_e32 v174, v79
	v_mov_b32_e32 v175, v71
	v_pk_fma_f32 v[170:171], v[170:171], v[170:171], v[172:173]
	v_mov_b32_e32 v172, v78
	v_mov_b32_e32 v173, v70
	v_pk_mul_f32 v[174:175], v[174:175], v[174:175]
	v_mov_b32_e32 v176, v75
	v_pk_fma_f32 v[172:173], v[172:173], v[172:173], v[174:175]
	v_mov_b32_e32 v174, v77
	v_mov_b32_e32 v175, v69
	v_pk_add_f32 v[170:171], v[170:171], v[172:173]
	v_mov_b32_e32 v172, v76
	v_mov_b32_e32 v173, v68
	v_pk_mul_f32 v[174:175], v[174:175], v[174:175]
	v_mov_b32_e32 v177, v67
	v_pk_fma_f32 v[172:173], v[172:173], v[172:173], v[174:175]
	v_mov_b32_e32 v174, v74
	v_mov_b32_e32 v175, v66
	v_pk_mul_f32 v[176:177], v[176:177], v[176:177]
	s_nop 0
	v_pk_fma_f32 v[174:175], v[174:175], v[174:175], v[176:177]
	s_nop 0
	v_pk_add_f32 v[172:173], v[172:173], v[174:175]
	s_nop 0
	v_pk_add_f32 v[170:171], v[170:171], v[172:173]
	s_nop 0
	v_add_f32_e32 v219, v170, v171
	v_add_u32_e32 v170, 0x80, v146
	v_ashrrev_i32_e32 v171, 31, v170
	v_lshlrev_b64 v[172:173], 11, v[170:171]
	v_lshl_add_u64 v[172:173], v[158:159], 0, v[172:173]
	v_mov_b64_e32 v[174:175], v[172:173]
	flat_load_dwordx4 v[176:179], v[174:175]
	flat_load_dwordx4 v[232:235], v[174:175] offset:256
	s_waitcnt vmcnt(0) lgkmcnt(0)
	v_lshlrev_b32_e32 v186, 16, v176
	v_and_b32_e32 v187, 0xffff0000, v176
	v_lshlrev_b32_e32 v188, 16, v177
	v_and_b32_e32 v189, 0xffff0000, v177
	v_lshlrev_b32_e32 v190, 16, v178
	v_and_b32_e32 v191, 0xffff0000, v178
	v_lshlrev_b32_e32 v192, 16, v179
	v_and_b32_e32 v193, 0xffff0000, v179
	v_mov_b64_e32 v[176:177], v[240:241]
	v_mov_b64_e32 v[178:179], v[242:243]
	v_mov_b64_e32 v[182:183], v[236:237]
	v_mov_b64_e32 v[184:185], v[238:239]
	s_waitcnt vmcnt(0)
;     __device__ __forceinline__ void fused(f32x4 (&acc)[2][2][4][2], const Unit& u, int wr, int wc, int fr, int fq, LAS unsigned char* lds, int wid, int lane) const {
;     ...
; #pragma unroll
;             for (int m = 0; m < 4; ++m) {
;                 const bf16_t* hrow = hb + (size_t)(row0 + ai * HALF + m * 16) * DM + col0;
;                 asm volatile("" : "+v"(hrow) : "v"(dep));
;                 const float r1 = rv[ai][m];
;                 float q = 0.f;
; #pragma unroll
;                 for (int bj = 0; bj < 2; ++bj) {
;                     const u32x4 hv = *(const u32x4*)(hrow + bj * HALF);
;                     const f32x4 h0 = (f32x4){__uint_as_float(hv.x << 16), __uint_as_float(hv.x & 0xffff0000u), __uint_as_float(hv.y << 16), __uint_as_float(hv.y & 0xffff0000u)};
;                     const f32x4 h1 = (f32x4){__uint_as_float(hv.z << 16), __uint_as_float(hv.z & 0xffff0000u), __uint_as_float(hv.w << 16), __uint_as_float(hv.w & 0xffff0000u)};
;                     const f32x4 gg0 = *(const f32x4*)(gpost + col0 + bj * HALF), gg1 = *(const f32x4*)(gpost + col0 + bj * HALF + 4);
;                     f32x4 x0 = h0 + acc[ai][bj][m][0] * r1 * gg0, x1 = h1 + acc[ai][bj][m][1] * r1 * gg1;
;                     acc[ai][bj][m][0] = x0; acc[ai][bj][m][1] = x1;
;                     q += ((x0[0] * x0[0] + x0[1] * x0[1]) + (x0[2] * x0[2] + x0[3] * x0[3])) + ((x1[0] * x1[0] + x1[1] * x1[1]) + (x1[2] * x1[2] + x1[3] * x1[3]));
;                 }
;                 sv[ai][m] = q;
;                 dep = q;
	v_pk_fma_f32 v[62:63], v[64:65], v[184:185], v[188:189]
	v_pk_fma_f32 v[64:65], v[194:195], v[182:183], v[186:187]
	v_pk_mul_f32 v[182:183], v[58:59], v[168:169] op_sel_hi:[1,0]
	v_pk_fma_f32 v[58:59], v[60:61], v[178:179], v[192:193]
	v_pk_fma_f32 v[60:61], v[182:183], v[176:177], v[190:191]
	v_mov_b64_e32 v[174:175], v[232:233]
	v_mov_b64_e32 v[176:177], v[234:235]
	v_pk_mul_f32 v[192:193], v[54:55], v[168:169] op_sel_hi:[1,0]
	s_waitcnt vmcnt(0) lgkmcnt(0)
	v_lshlrev_b32_e32 v178, 16, v174
	v_and_b32_e32 v179, 0xffff0000, v174
	v_lshlrev_b32_e32 v186, 16, v175
	v_and_b32_e32 v187, 0xffff0000, v175
	v_lshlrev_b32_e32 v188, 16, v176
	v_and_b32_e32 v189, 0xffff0000, v176
	v_lshlrev_b32_e32 v190, 16, v177
	v_and_b32_e32 v191, 0xffff0000, v177
	v_mov_b64_e32 v[174:175], v[248:249]
	v_mov_b64_e32 v[176:177], v[250:251]
	v_mov_b64_e32 v[182:183], v[244:245]
	v_mov_b64_e32 v[184:185], v[246:247]
	s_waitcnt vmcnt(0)
	v_pk_fma_f32 v[54:55], v[56:57], v[184:185], v[186:187]
	v_pk_fma_f32 v[56:57], v[192:193], v[182:183], v[178:179]
	v_pk_mul_f32 v[178:179], v[50:51], v[168:169] op_sel_hi:[1,0]
	v_pk_fma_f32 v[50:51], v[52:53], v[176:177], v[190:191]
	v_mov_b32_e32 v176, v65
	v_mov_b32_e32 v177, v57
	v_pk_fma_f32 v[52:53], v[178:179], v[174:175], v[188:189]
	v_mov_b32_e32 v174, v64
	v_mov_b32_e32 v175, v56
	v_pk_mul_f32 v[176:177], v[176:177], v[176:177]
	v_mov_b32_e32 v178, v63
	v_mov_b32_e32 v179, v55
	v_pk_fma_f32 v[174:175], v[174:175], v[174:175], v[176:177]
	v_mov_b32_e32 v176, v62
	v_mov_b32_e32 v177, v54
	v_pk_mul_f32 v[178:179], v[178:179], v[178:179]
	v_mov_b32_e32 v182, v59
	v_pk_fma_f32 v[176:177], v[176:177], v[176:177], v[178:179]
	v_mov_b32_e32 v178, v61
	v_mov_b32_e32 v179, v53
	v_pk_add_f32 v[174:175], v[174:175], v[176:177]
	v_mov_b32_e32 v176, v60
	v_mov_b32_e32 v177, v52
	v_pk_mul_f32 v[178:179], v[178:179], v[178:179]
	v_mov_b32_e32 v183, v51
	v_pk_fma_f32 v[176:177], v[176:177], v[176:177], v[178:179]
	v_mov_b32_e32 v178, v58
	v_mov_b32_e32 v179, v50
	v_pk_mul_f32 v[182:183], v[182:183], v[182:183]
	v_pk_mul_f32 v[168:169], v[46:47], v[198:199] op_sel_hi:[1,0]
	v_pk_fma_f32 v[178:179], v[178:179], v[178:179], v[182:183]
	s_nop 0
	v_pk_add_f32 v[176:177], v[176:177], v[178:179]
	s_nop 0
	v_pk_add_f32 v[174:175], v[174:175], v[176:177]
	s_nop 0
	v_add_f32_e32 v220, v174, v175
	v_add_u32_e32 v174, 0x90, v146
	v_ashrrev_i32_e32 v175, 31, v174
	v_lshlrev_b64 v[176:177], 11, v[174:175]
	v_lshl_add_u64 v[176:177], v[158:159], 0, v[176:177]
	v_mov_b64_e32 v[178:179], v[176:177]
	flat_load_dwordx4 v[182:185], v[178:179]
	flat_load_dwordx4 v[232:235], v[178:179] offset:256
	s_waitcnt vmcnt(0) lgkmcnt(0)
	v_lshlrev_b32_e32 v190, 16, v182
	v_and_b32_e32 v191, 0xffff0000, v182
	v_lshlrev_b32_e32 v192, 16, v183
	v_and_b32_e32 v193, 0xffff0000, v183
	v_lshlrev_b32_e32 v194, 16, v184
	v_and_b32_e32 v195, 0xffff0000, v184
	v_lshlrev_b32_e32 v196, 16, v185
	v_and_b32_e32 v197, 0xffff0000, v185
	v_mov_b64_e32 v[182:183], v[240:241]
	v_mov_b64_e32 v[184:185], v[242:243]
	v_mov_b64_e32 v[186:187], v[236:237]
	v_mov_b64_e32 v[188:189], v[238:239]
	s_waitcnt vmcnt(0)
	v_pk_fma_f32 v[46:47], v[48:49], v[188:189], v[192:193]
	v_pk_fma_f32 v[48:49], v[168:169], v[186:187], v[190:191]
	v_pk_mul_f32 v[168:169], v[42:43], v[198:199] op_sel_hi:[1,0]
	v_pk_fma_f32 v[42:43], v[44:45], v[184:185], v[196:197]
	v_pk_fma_f32 v[44:45], v[168:169], v[182:183], v[194:195]
	v_mov_b64_e32 v[182:183], v[232:233]
	v_mov_b64_e32 v[184:185], v[234:235]
	s_waitcnt vmcnt(0) lgkmcnt(0)
	v_lshlrev_b32_e32 v178, 16, v182
	v_and_b32_e32 v179, 0xffff0000, v182
	v_lshlrev_b32_e32 v168, 16, v183
	v_and_b32_e32 v169, 0xffff0000, v183
	v_lshlrev_b32_e32 v192, 16, v184
	v_and_b32_e32 v193, 0xffff0000, v184
	v_lshlrev_b32_e32 v182, 16, v185
	v_and_b32_e32 v183, 0xffff0000, v185
	v_mov_b64_e32 v[184:185], v[248:249]
	v_mov_b64_e32 v[186:187], v[250:251]
	v_mov_b64_e32 v[188:189], v[244:245]
	v_mov_b64_e32 v[190:191], v[246:247]
	s_waitcnt vmcnt(1)
	v_pk_fma_f32 v[182:183], v[36:37], v[186:187], v[182:183]
	s_waitcnt vmcnt(0)
	v_pk_fma_f32 v[178:179], v[38:39], v[188:189], v[178:179]
	v_pk_fma_f32 v[168:169], v[40:41], v[190:191], v[168:169]
	v_mov_b32_e32 v36, v49
	v_mov_b32_e32 v37, v179
	v_pk_fma_f32 v[184:185], v[34:35], v[184:185], v[192:193]
	v_mov_b32_e32 v34, v48
	v_mov_b32_e32 v35, v178
	v_pk_mul_f32 v[36:37], v[36:37], v[36:37]
	v_mov_b32_e32 v38, v47
	v_mov_b32_e32 v39, v169
	v_pk_fma_f32 v[34:35], v[34:35], v[34:35], v[36:37]
	v_mov_b32_e32 v36, v46
	v_mov_b32_e32 v37, v168
	v_pk_mul_f32 v[38:39], v[38:39], v[38:39]
	v_mov_b32_e32 v40, v43
	v_pk_fma_f32 v[36:37], v[36:37], v[36:37], v[38:39]
	v_mov_b32_e32 v38, v45
	v_mov_b32_e32 v39, v185
	v_pk_add_f32 v[34:35], v[34:35], v[36:37]
	v_mov_b32_e32 v36, v44
	v_mov_b32_e32 v37, v184
	v_pk_mul_f32 v[38:39], v[38:39], v[38:39]
	v_mov_b32_e32 v41, v183
	v_pk_fma_f32 v[36:37], v[36:37], v[36:37], v[38:39]
	v_mov_b32_e32 v38, v42
	v_mov_b32_e32 v39, v182
	v_pk_mul_f32 v[40:41], v[40:41], v[40:41]
	v_add_u32_e32 v186, 0xa0, v146
	v_pk_fma_f32 v[38:39], v[38:39], v[38:39], v[40:41]
	v_ashrrev_i32_e32 v187, 31, v186
	v_pk_add_f32 v[36:37], v[36:37], v[38:39]
	s_nop 0
	v_pk_add_f32 v[34:35], v[34:35], v[36:37]
	s_nop 0
	v_add_f32_e32 v221, v34, v35
	v_lshlrev_b64 v[34:35], 11, v[186:187]
	v_lshl_add_u64 v[188:189], v[158:159], 0, v[34:35]
	v_mov_b64_e32 v[34:35], v[188:189]
	flat_load_dwordx4 v[36:39], v[34:35]
	flat_load_dwordx4 v[232:235], v[34:35] offset:256
	s_waitcnt vmcnt(0) lgkmcnt(0)
; __device__ __forceinline__ float xhalf_sum(float x) { auto t = __builtin_amdgcn_permlane32_swap(__float_as_uint(x), __float_as_uint(x), false, false); return __uint_as_float(t[0]) + __uint_as_float(t[1]); }
;     __device__ __forceinline__ void exchange(int e, float (&sv)[2][4], float (&rv)[2][4], const Unit& u, int wr, int wc, int fr, int fq, LAS unsigned char* lds, int wid, int lane) const {
;     ...
; #pragma unroll
;         for (int ai = 0; ai < 2; ++ai)
; #pragma unroll
;             for (int m = 0; m < 4; ++m) {
;                 float v = sv[ai][m];
;                 { auto t1 = __builtin_amdgcn_permlane16_swap(__float_as_uint(v), __float_as_uint(v), false, false); v = __uint_as_float(t1[0]) + __uint_as_float(t1[1]); }
;                 v = xhalf_sum(v);
;                 if (fq == 0) P[(ai * HALF + wr * 64 + m * 16 + fr) * 4 + wc] = v;
;             }
;     __device__ __forceinline__ void fused(f32x4 (&acc)[2][2][4][2], const Unit& u, int wr, int wc, int fr, int fq, LAS unsigned char* lds, int wid, int lane) const {
;     ...
; #pragma unroll
;             for (int m = 0; m < 4; ++m) {
;                 const bf16_t* hrow = hb + (size_t)(row0 + ai * HALF + m * 16) * DM + col0;
;                 asm volatile("" : "+v"(hrow) : "v"(dep));
;                 const float r1 = rv[ai][m];
;                 float q = 0.f;
; #pragma unroll
;                 for (int bj = 0; bj < 2; ++bj) {
;                     const u32x4 hv = *(const u32x4*)(hrow + bj * HALF);
;                     const f32x4 h0 = (f32x4){__uint_as_float(hv.x << 16), __uint_as_float(hv.x & 0xffff0000u), __uint_as_float(hv.y << 16), __uint_as_float(hv.y & 0xffff0000u)};
;                     const f32x4 h1 = (f32x4){__uint_as_float(hv.z << 16), __uint_as_float(hv.z & 0xffff0000u), __uint_as_float(hv.w << 16), __uint_as_float(hv.w & 0xffff0000u)};
;                     const f32x4 gg0 = *(const f32x4*)(gpost + col0 + bj * HALF), gg1 = *(const f32x4*)(gpost + col0 + bj * HALF + 4);
;                     f32x4 x0 = h0 + acc[ai][bj][m][0] * r1 * gg0, x1 = h1 + acc[ai][bj][m][1] * r1 * gg1;
;                     acc[ai][bj][m][0] = x0; acc[ai][bj][m][1] = x1;
;                     q += ((x0[0] * x0[0] + x0[1] * x0[1]) + (x0[2] * x0[2] + x0[3] * x0[3])) + ((x1[0] * x1[0] + x1[1] * x1[1]) + (x1[2] * x1[2] + x1[3] * x1[3]));
;                 }
;                 sv[ai][m] = q;
;                 dep = q;
	v_lshlrev_b32_e32 v40, 16, v36
	v_and_b32_e32 v41, 0xffff0000, v36
	v_lshlrev_b32_e32 v190, 16, v37
	v_and_b32_e32 v191, 0xffff0000, v37
	v_lshlrev_b32_e32 v196, 16, v38
	v_and_b32_e32 v197, 0xffff0000, v38
	v_lshlrev_b32_e32 v198, 16, v39
	v_and_b32_e32 v199, 0xffff0000, v39
	v_mov_b64_e32 v[36:37], v[240:241]
	v_mov_b64_e32 v[38:39], v[242:243]
	v_mov_b64_e32 v[192:193], v[236:237]
	v_mov_b64_e32 v[194:195], v[238:239]
	s_waitcnt vmcnt(1)
	v_pk_fma_f32 v[196:197], v[26:27], v[36:37], v[196:197]
	s_waitcnt vmcnt(0)
	v_pk_fma_f32 v[190:191], v[32:33], v[194:195], v[190:191]
	v_pk_fma_f32 v[194:195], v[28:29], v[38:39], v[198:199]
	v_mov_b64_e32 v[26:27], v[232:233]
	v_mov_b64_e32 v[28:29], v[234:235]
	v_pk_fma_f32 v[192:193], v[30:31], v[192:193], v[40:41]
	s_waitcnt vmcnt(0) lgkmcnt(0)
	v_lshlrev_b32_e32 v34, 16, v26
	v_and_b32_e32 v35, 0xffff0000, v26
	v_lshlrev_b32_e32 v36, 16, v27
	v_and_b32_e32 v37, 0xffff0000, v27
	v_lshlrev_b32_e32 v38, 16, v28
	v_and_b32_e32 v39, 0xffff0000, v28
	v_lshlrev_b32_e32 v40, 16, v29
	v_and_b32_e32 v41, 0xffff0000, v29
	v_mov_b64_e32 v[26:27], v[248:249]
	v_mov_b64_e32 v[28:29], v[250:251]
	v_mov_b64_e32 v[30:31], v[244:245]
	v_mov_b64_e32 v[32:33], v[246:247]
	s_waitcnt vmcnt(1)
	v_pk_fma_f32 v[202:203], v[20:21], v[28:29], v[40:41]
	s_waitcnt vmcnt(0)
	v_pk_fma_f32 v[200:201], v[22:23], v[30:31], v[34:35]
	v_pk_fma_f32 v[198:199], v[24:25], v[32:33], v[36:37]
	v_mov_b32_e32 v20, v193
	v_mov_b32_e32 v21, v201
	v_pk_fma_f32 v[204:205], v[18:19], v[26:27], v[38:39]
	v_mov_b32_e32 v18, v192
	v_mov_b32_e32 v19, v200
	v_pk_mul_f32 v[20:21], v[20:21], v[20:21]
	v_mov_b32_e32 v22, v191
	v_mov_b32_e32 v23, v199
	v_pk_fma_f32 v[18:19], v[18:19], v[18:19], v[20:21]
	v_mov_b32_e32 v20, v190
	v_mov_b32_e32 v21, v198
	v_pk_mul_f32 v[22:23], v[22:23], v[22:23]
	v_mov_b32_e32 v24, v195
	v_pk_fma_f32 v[20:21], v[20:21], v[20:21], v[22:23]
	v_mov_b32_e32 v22, v197
	v_mov_b32_e32 v23, v205
	v_pk_add_f32 v[18:19], v[18:19], v[20:21]
	v_mov_b32_e32 v20, v196
	v_mov_b32_e32 v21, v204
	v_pk_mul_f32 v[22:23], v[22:23], v[22:23]
	v_mov_b32_e32 v25, v203
	v_pk_fma_f32 v[20:21], v[20:21], v[20:21], v[22:23]
	v_mov_b32_e32 v22, v194
	v_mov_b32_e32 v23, v202
	v_pk_mul_f32 v[24:25], v[24:25], v[24:25]
	s_nop 0
	v_pk_fma_f32 v[22:23], v[22:23], v[22:23], v[24:25]
	s_nop 0
	v_pk_add_f32 v[20:21], v[20:21], v[22:23]
	s_nop 0
	v_pk_add_f32 v[18:19], v[18:19], v[20:21]
	s_nop 0
	v_add_f32_e32 v154, v18, v19
	v_lshlrev_b64 v[18:19], 11, v[206:207]
	v_lshl_add_u64 v[158:159], v[158:159], 0, v[18:19]
	v_mov_b64_e32 v[18:19], v[158:159]
	flat_load_dwordx4 v[38:41], v[18:19]
	v_mov_b64_e32 v[30:31], v[240:241]
	v_mov_b64_e32 v[32:33], v[242:243]
	v_mov_b64_e32 v[34:35], v[236:237]
	v_mov_b64_e32 v[36:37], v[238:239]
	flat_load_dwordx4 v[26:29], v[18:19] offset:256
	s_nop 0
	v_mov_b64_e32 v[18:19], v[248:249]
	v_mov_b64_e32 v[20:21], v[250:251]
	v_mov_b64_e32 v[22:23], v[244:245]
	v_mov_b64_e32 v[24:25], v[246:247]
	v_mov_b32_e32 v156, v216
	s_nop 1
	v_permlane16_swap_b32_e32 v216, v156
	v_add_f32_e32 v156, v216, v156
	v_mov_b32_e32 v157, v156
	s_nop 1
	v_permlane32_swap_b32_e32 v156, v157
	s_and_saveexec_b64 s[10:11], s[4:5]
	v_add_f32_e32 v156, v156, v157
	ds_write_b32 v212, v156
	s_or_b64 exec, exec, s[10:11]
	v_mov_b32_e32 v156, v217
	s_nop 1
	v_permlane16_swap_b32_e32 v217, v156
	v_add_f32_e32 v156, v217, v156
	v_mov_b32_e32 v157, v156
	s_nop 1
	v_permlane32_swap_b32_e32 v156, v157
	s_and_saveexec_b64 s[10:11], s[4:5]
	v_add_f32_e32 v156, v156, v157
	ds_write_b32 v212, v156 offset:256
	s_or_b64 exec, exec, s[10:11]
	v_mov_b32_e32 v156, v218
	s_nop 1
	v_permlane16_swap_b32_e32 v218, v156
	v_add_f32_e32 v156, v218, v156
	v_mov_b32_e32 v157, v156
	s_nop 1
	v_permlane32_swap_b32_e32 v156, v157
	s_and_saveexec_b64 s[10:11], s[4:5]
	v_add_f32_e32 v156, v156, v157
	ds_write_b32 v212, v156 offset:512
	s_or_b64 exec, exec, s[10:11]
	v_mov_b32_e32 v156, v219
	s_nop 1
	v_permlane16_swap_b32_e32 v219, v156
	v_add_f32_e32 v156, v219, v156
	v_mov_b32_e32 v157, v156
	s_nop 1
	v_permlane32_swap_b32_e32 v156, v157
	s_and_saveexec_b64 s[10:11], s[4:5]
	v_add_f32_e32 v156, v156, v157
	ds_write_b32 v212, v156 offset:768
	s_or_b64 exec, exec, s[10:11]
	v_mov_b32_e32 v156, v220
	s_nop 1
	v_permlane16_swap_b32_e32 v220, v156
	v_add_f32_e32 v156, v220, v156
	v_mov_b32_e32 v157, v156
	s_nop 1
	v_permlane32_swap_b32_e32 v156, v157
	s_and_saveexec_b64 s[10:11], s[4:5]
	v_add_f32_e32 v156, v156, v157
	ds_write_b32 v212, v156 offset:2048
	s_or_b64 exec, exec, s[10:11]
	v_mov_b32_e32 v156, v221
	s_nop 1
	v_permlane16_swap_b32_e32 v221, v156
	v_add_f32_e32 v156, v221, v156
	v_mov_b32_e32 v157, v156
	s_nop 1
	v_permlane32_swap_b32_e32 v156, v157
	s_and_saveexec_b64 s[10:11], s[4:5]
	v_add_f32_e32 v156, v156, v157
	ds_write_b32 v212, v156 offset:2304
	s_or_b64 exec, exec, s[10:11]
	v_mov_b32_e32 v156, v154
	s_nop 1
	v_permlane16_swap_b32_e32 v154, v156
	v_add_f32_e32 v154, v154, v156
	v_mov_b32_e32 v156, v154
	s_nop 1
	v_permlane32_swap_b32_e32 v154, v156
	s_and_saveexec_b64 s[10:11], s[4:5]
	v_add_f32_e32 v154, v154, v156
	ds_write_b32 v212, v154 offset:2560
	s_or_b64 exec, exec, s[10:11]
	v_mov_b32_e32 v154, v155
	s_waitcnt vmcnt(0) lgkmcnt(0)
; #define LAS __attribute__((address_space(3)))
; __device__ __forceinline__ float xhalf_sum(float x) { auto t = __builtin_amdgcn_permlane32_swap(__float_as_uint(x), __float_as_uint(x), false, false); return __uint_as_float(t[0]) + __uint_as_float(t[1]); }
;     __device__ __forceinline__ void exchange(int e, float (&sv)[2][4], float (&rv)[2][4], const Unit& u, int wr, int wc, int fr, int fq, LAS unsigned char* lds, int wid, int lane) const {
;     ...
;                 float v = sv[ai][m];
;                 { auto t1 = __builtin_amdgcn_permlane16_swap(__float_as_uint(v), __float_as_uint(v), false, false); v = __uint_as_float(t1[0]) + __uint_as_float(t1[1]); }
;                 v = xhalf_sum(v);
;                 if (fq == 0) P[(ai * HALF + wr * 64 + m * 16 + fr) * 4 + wc] = v;
;             }
;         asm volatile("s_waitcnt lgkmcnt(0)" ::: "memory"); __builtin_amdgcn_s_barrier(); asm volatile("" ::: "memory");
;         const int tid = wid * 64 + lane;
;         if (tid < 256) {
;             const f32x4 pp = *(const LAS f32x4*)(P + tid * 4);
;             __hip_atomic_store(xbuf + ((size_t)u.pm * 256 + tid) * 4 + u.pn, (pp[0] + pp[1]) + (pp[2] + pp[3]), __ATOMIC_RELAXED, __HIP_MEMORY_SCOPE_AGENT);
;     __device__ __forceinline__ void fused(f32x4 (&acc)[2][2][4][2], const Unit& u, int wr, int wc, int fr, int fq, LAS unsigned char* lds, int wid, int lane) const {
;     ...
;                     const u32x4 hv = *(const u32x4*)(hrow + bj * HALF);
;                     const f32x4 h0 = (f32x4){__uint_as_float(hv.x << 16), __uint_as_float(hv.x & 0xffff0000u), __uint_as_float(hv.y << 16), __uint_as_float(hv.y & 0xffff0000u)};
;                     const f32x4 h1 = (f32x4){__uint_as_float(hv.z << 16), __uint_as_float(hv.z & 0xffff0000u), __uint_as_float(hv.w << 16), __uint_as_float(hv.w & 0xffff0000u)};
;                     const f32x4 gg0 = *(const f32x4*)(gpost + col0 + bj * HALF), gg1 = *(const f32x4*)(gpost + col0 + bj * HALF + 4);
;                     f32x4 x0 = h0 + acc[ai][bj][m][0] * r1 * gg0, x1 = h1 + acc[ai][bj][m][1] * r1 * gg1;
;                     acc[ai][bj][m][0] = x0; acc[ai][bj][m][1] = x1;
;                     q += ((x0[0] * x0[0] + x0[1] * x0[1]) + (x0[2] * x0[2] + x0[3] * x0[3])) + ((x1[0] * x1[0] + x1[1] * x1[1]) + (x1[2] * x1[2] + x1[3] * x1[3]));
;                 }
;                 sv[ai][m] = q;
;                 dep = q;
	v_lshlrev_b32_e32 v156, 16, v38
	v_and_b32_e32 v157, 0xffff0000, v38
	v_lshlrev_b32_e32 v38, 16, v39
	v_and_b32_e32 v39, 0xffff0000, v39
	v_pk_mul_f32 v[16:17], v[16:17], v[154:155] op_sel_hi:[1,0]
	v_pk_mul_f32 v[218:219], v[14:15], v[154:155] op_sel_hi:[1,0]
	v_lshlrev_b32_e32 v216, 16, v40
	v_and_b32_e32 v217, 0xffff0000, v40
	v_lshlrev_b32_e32 v40, 16, v41
	v_and_b32_e32 v41, 0xffff0000, v41
	v_pk_fma_f32 v[14:15], v[16:17], v[36:37], v[38:39]
	v_pk_fma_f32 v[16:17], v[218:219], v[34:35], v[156:157]
	v_pk_mul_f32 v[12:13], v[12:13], v[154:155] op_sel_hi:[1,0]
	v_pk_mul_f32 v[34:35], v[10:11], v[154:155] op_sel_hi:[1,0]
	v_pk_fma_f32 v[10:11], v[12:13], v[32:33], v[40:41]
	v_pk_fma_f32 v[12:13], v[34:35], v[30:31], v[216:217]
	v_mul_f32_e32 v30, v17, v17
	v_mul_f32_e32 v31, v15, v15
	v_fmac_f32_e32 v30, v16, v16
	v_fmac_f32_e32 v31, v14, v14
	v_add_f32_e32 v30, v30, v31
	v_mul_f32_e32 v31, v13, v13
	v_mul_f32_e32 v32, v11, v11
	v_fmac_f32_e32 v31, v12, v12
	v_fmac_f32_e32 v32, v10, v10
	v_add_f32_e32 v31, v31, v32
	v_add_f32_e32 v36, v30, v31
	v_lshlrev_b32_e32 v30, 16, v26
	v_and_b32_e32 v31, 0xffff0000, v26
	v_lshlrev_b32_e32 v26, 16, v27
	v_and_b32_e32 v27, 0xffff0000, v27
	v_pk_mul_f32 v[8:9], v[8:9], v[154:155] op_sel_hi:[1,0]
	v_pk_mul_f32 v[34:35], v[6:7], v[154:155] op_sel_hi:[1,0]
	v_lshlrev_b32_e32 v32, 16, v28
	v_and_b32_e32 v33, 0xffff0000, v28
	v_lshlrev_b32_e32 v28, 16, v29
	v_and_b32_e32 v29, 0xffff0000, v29
	v_pk_fma_f32 v[6:7], v[8:9], v[24:25], v[26:27]
	v_pk_fma_f32 v[8:9], v[34:35], v[22:23], v[30:31]
	v_pk_mul_f32 v[4:5], v[4:5], v[154:155] op_sel_hi:[1,0]
	v_pk_mul_f32 v[22:23], v[2:3], v[154:155] op_sel_hi:[1,0]
	v_pk_fma_f32 v[2:3], v[4:5], v[20:21], v[28:29]
	v_pk_fma_f32 v[4:5], v[22:23], v[18:19], v[32:33]
	v_mul_f32_e32 v18, v9, v9
	v_mul_f32_e32 v19, v7, v7
	v_fmac_f32_e32 v18, v8, v8
	v_fmac_f32_e32 v19, v6, v6
	v_add_f32_e32 v18, v18, v19
	v_mul_f32_e32 v19, v5, v5
	v_mul_f32_e32 v20, v3, v3
	v_fmac_f32_e32 v19, v4, v4
	v_fmac_f32_e32 v20, v2, v2
	v_add_f32_e32 v19, v19, v20
	v_add_f32_e32 v18, v18, v19
	v_add_f32_e32 v18, v36, v18
	v_mov_b32_e32 v19, v18
	s_nop 1
	v_permlane16_swap_b32_e32 v18, v19
	v_add_f32_e32 v18, v18, v19
	v_mov_b32_e32 v19, v18
	s_nop 1
	v_permlane32_swap_b32_e32 v18, v19
	s_and_saveexec_b64 s[10:11], s[4:5]
	v_add_f32_e32 v18, v18, v19
	ds_write_b32 v212, v18 offset:2816
	s_or_b64 exec, exec, s[10:11]
	s_waitcnt lgkmcnt(0)
	s_barrier
	s_and_saveexec_b64 s[10:11], s[6:7]
	s_cbranch_execz .LBB0_1452
	ds_read_b128 v[18:21], v215
	s_lshl_b64 s[42:43], s[28:29], 12
	v_lshl_add_u64 v[22:23], v[140:141], 0, s[42:43]
	s_ashr_i32 s27, s26, 31
	v_lshl_add_u64 v[22:23], s[26:27], 2, v[22:23]
	s_waitcnt lgkmcnt(0)
	v_mov_b32_e32 v24, v19
	v_mov_b32_e32 v25, v20
	v_mov_b32_e32 v19, v21
	v_pk_add_f32 v[18:19], v[24:25], v[18:19]
	s_nop 0
	v_pk_add_f32 v[18:19], v[18:19], v[18:19] op_sel:[0,1] op_sel_hi:[1,0]
	global_store_dword v[22:23], v18, off sc1
